# t18 + dependency counter read prefetched during the in-proj store drain; acquire invalidate only when a wait was needed
# speedup vs baseline: 1.0127x; 1.0045x over previous
.LBB0_316:
	v_mov_b32_e32 v2, 0x3800
	global_load_dword v3, v2, s[96:97] sc1
	s_waitcnt vmcnt(0)
	v_readlane_b32 s78, v247, 30
	v_readlane_b32 s80, v247, 28
	v_readlane_b32 s82, v247, 26
	s_mov_b32 s65, s86
	s_mov_b64 s[70:71], s[94:95]
	s_mov_b32 s69, s87
	s_mov_b64 s[72:73], s[96:97]
	s_mov_b32 s74, s98
	v_readlane_b32 s75, v247, 32
	s_mov_b32 s76, s99
	v_readlane_b32 s79, v247, 31
	v_readlane_b32 s81, v247, 29
	v_readlane_b32 s83, v247, 27
	s_barrier

.Lsyn_pub_done:
	s_or_b64 exec, exec, s[2:3]
	s_cmpk_lg_i32 s92, 0x100
	s_cbranch_scc1 .Lsyn_slow
	s_mov_b32 s100, 1
	v_cmp_eq_u32_e32 vcc, 0, v161
	s_and_saveexec_b64 s[2:3], vcc
	s_cbranch_execz .Lsyn_wait_done
	v_mov_b32_e32 v0, 0x3800
	s_mov_b32 s4, 0
	s_lshl_b32 s5, s92, 3
	v_cmp_le_u32_e32 vcc, s5, v3
	s_cbranch_vccnz .Lsyn_wait_done
